# cand18 + item pipeline: per-row gain loads issued ahead of the other item's row loads (store half waits vmcnt(16) instead of vmcnt(0))
# baseline (speedup 1.0000x reference)
.LBB0_43:
	s_lshr_b32 s48, s34, 6
	v_cvt_f32_u32_e32 v1, s48
	s_sub_i32 s49, 0, s48
	s_abs_i32 s47, s73
	s_ashr_i32 s46, s73, 31
	v_rcp_iflag_f32_e32 v1, v1
	v_mov_b32_e32 v141, 0
	s_mov_b32 s35, 0
	v_lshlrev_b32_e32 v138, 2, v194
	v_mul_f32_e32 v1, 0x4f7ffffe, v1
	v_cvt_u32_f32_e32 v1, v1
	v_mov_b32_e32 v139, v141
	v_mov_b32_e32 v3, v2
	v_lshlrev_b32_e32 v140, 1, v193
	v_readfirstlane_b32 s50, v1
	s_mul_i32 s49, s49, s50
	s_mul_hi_u32 s49, s50, s49
	s_add_i32 s50, s50, s49
	s_mul_hi_u32 s49, s47, s50
	s_mul_i32 s50, s49, s48
	s_sub_i32 s47, s47, s50
	s_add_i32 s51, s49, 1
	s_sub_i32 s50, s47, s48
	s_cmp_ge_u32 s47, s48
	s_cselect_b32 s49, s51, s49
	s_cselect_b32 s47, s50, s47
	s_add_i32 s50, s49, 1
	s_cmp_ge_u32 s47, s48
	s_cselect_b32 s47, s50, s49
	s_xor_b32 s47, s47, s46
	s_sub_i32 s49, s47, s46
	s_lshl_b32 s46, s49, 6
	v_or_b32_e32 v1, s46, v137
	v_lshlrev_b32_e32 v245, 2, v1
	s_ashr_i32 s46, s46, 31
	s_mul_i32 s50, s46, s34
	v_mad_u64_u32 v[4:5], s[46:47], v1, s34, 0
	v_add_u32_e32 v5, s50, v5
	s_mul_i32 s49, s49, s48
	s_waitcnt lgkmcnt(0)
	v_lshl_add_u64 v[4:5], v[4:5], 2, s[2:3]
	s_sub_i32 s2, s73, s49
	s_lshl_b32 s2, s2, 6
	s_ashr_i32 s3, s2, 31
	v_lshl_add_u64 v[4:5], s[2:3], 2, v[4:5]
	v_lshl_add_u64 v[4:5], v[4:5], 0, v[138:139]
	s_lshl_b64 s[2:3], s[34:35], 4
	v_lshl_add_u64 v[14:15], v[4:5], 0, s[2:3]
	global_load_dwordx4 v[6:9], v[4:5], off nt
	global_load_dwordx4 v[10:13], v[14:15], off nt
	v_lshl_add_u64 v[4:5], v[14:15], 0, s[2:3]
	v_lshl_add_u64 v[22:23], v[4:5], 0, s[2:3]
	global_load_dwordx4 v[14:17], v[4:5], off nt
	global_load_dwordx4 v[18:21], v[22:23], off nt
	v_lshl_add_u64 v[4:5], v[22:23], 0, s[2:3]
	v_lshl_add_u64 v[30:31], v[4:5], 0, s[2:3]
	global_load_dwordx4 v[22:25], v[4:5], off nt
	global_load_dwordx4 v[26:29], v[30:31], off nt
	v_lshl_add_u64 v[4:5], v[30:31], 0, s[2:3]
	v_lshl_add_u64 v[38:39], v[4:5], 0, s[2:3]
	global_load_dwordx4 v[30:33], v[4:5], off nt
	global_load_dwordx4 v[34:37], v[38:39], off nt
	v_lshl_add_u64 v[4:5], v[38:39], 0, s[2:3]
	global_load_dwordx4 v[38:41], v[4:5], off nt
	v_lshl_add_u64 v[4:5], v[4:5], 0, s[2:3]
	global_load_dwordx4 v[46:49], v[4:5], off nt
	v_lshl_add_u64 v[4:5], v[4:5], 0, s[2:3]
	global_load_dwordx4 v[50:53], v[4:5], off nt
	v_lshl_add_u64 v[4:5], v[4:5], 0, s[2:3]
	global_load_dwordx4 v[62:65], v[4:5], off nt
	v_lshl_add_u64 v[4:5], v[4:5], 0, s[2:3]
	global_load_dwordx4 v[66:69], v[4:5], off nt
	v_lshl_add_u64 v[4:5], v[4:5], 0, s[2:3]
	global_load_dwordx4 v[82:85], v[4:5], off nt
	v_lshl_add_u64 v[4:5], v[4:5], 0, s[2:3]
	global_load_dwordx4 v[90:93], v[4:5], off nt
	v_lshl_add_u64 v[4:5], v[4:5], 0, s[2:3]
	global_load_dwordx4 v[102:105], v[4:5], off nt
	v_mov_b32_e32 v5, v136
	v_mov_b32_e32 v1, v2
	v_mov_b32_e32 v4, v2
	s_mov_b32 s46, 0x3e000000
	v_mbcnt_hi_u32_b32 v195, -1, v234
	s_mov_b32 s55, s14
	s_mov_b32 s54, s34
	s_branch .LBB0_47

.LBB0_47:
	s_cmp_eq_u64 s[44:45], 0
	s_cbranch_scc1 .Lgh_a_skip
	global_load_dword v203, v245, s[44:45]
	global_load_dword v204, v245, s[44:45] offset:16
	global_load_dword v205, v245, s[44:45] offset:32
	global_load_dword v206, v245, s[44:45] offset:48
	global_load_dword v207, v245, s[44:45] offset:64
	global_load_dword v208, v245, s[44:45] offset:80
	global_load_dword v209, v245, s[44:45] offset:96
	global_load_dword v210, v245, s[44:45] offset:112
	global_load_dword v211, v245, s[44:45] offset:128
	global_load_dword v212, v245, s[44:45] offset:144
	global_load_dword v213, v245, s[44:45] offset:160
	global_load_dword v215, v245, s[44:45] offset:176
	global_load_dword v216, v245, s[44:45] offset:192
	global_load_dword v242, v245, s[44:45] offset:208
	global_load_dword v243, v245, s[44:45] offset:224
	global_load_dword v244, v245, s[44:45] offset:240

.LBB0_63:
	s_lshr_b32 s60, s34, 6
	v_cvt_f32_u32_e32 v42, s60
	s_sub_i32 s63, 0, s60
	s_abs_i32 s62, s47
	s_ashr_i32 s61, s47, 31
	v_rcp_iflag_f32_e32 v42, v42
	v_mov_b32_e32 v139, v141
	v_mul_f32_e32 v42, 0x4f7ffffe, v42
	v_cvt_u32_f32_e32 v42, v42
	s_nop 0
	v_readfirstlane_b32 s76, v42
	s_mul_i32 s63, s63, s76
	s_mul_hi_u32 s63, s76, s63
	s_add_i32 s76, s76, s63
	s_mul_hi_u32 s63, s62, s76
	s_mul_i32 s76, s63, s60
	s_sub_i32 s62, s62, s76
	s_add_i32 s77, s63, 1
	s_sub_i32 s76, s62, s60
	s_cmp_ge_u32 s62, s60
	s_cselect_b32 s63, s77, s63
	s_cselect_b32 s62, s76, s62
	s_add_i32 s76, s63, 1
	s_cmp_ge_u32 s62, s60
	s_cselect_b32 s62, s76, s63
	s_xor_b32 s62, s62, s61
	s_sub_i32 s61, s62, s61
	s_mul_i32 s60, s61, s60
	s_lshl_b32 s61, s61, 6
	s_sub_i32 s62, s47, s60
	v_or_b32_e32 v42, s61, v137
	v_lshlrev_b32_e32 v246, 2, v42
	s_ashr_i32 s60, s61, 31
	s_mul_i32 s63, s60, s34
	v_mad_u64_u32 v[42:43], s[60:61], v42, s34, 0
	v_add_u32_e32 v43, s63, v43
	s_waitcnt lgkmcnt(0)
	v_lshl_add_u64 v[42:43], v[42:43], 2, s[2:3]
	s_lshl_b32 s2, s62, 6
	s_ashr_i32 s3, s2, 31
	v_lshl_add_u64 v[42:43], s[2:3], 2, v[42:43]
	v_lshl_add_u64 v[42:43], v[42:43], 0, v[138:139]
	s_lshl_b64 s[2:3], s[34:35], 4
	v_lshl_add_u64 v[58:59], v[42:43], 0, s[2:3]
	global_load_dwordx4 v[42:45], v[42:43], off nt
	s_nop 0
	global_load_dwordx4 v[54:57], v[58:59], off nt
	v_lshl_add_u64 v[58:59], v[58:59], 0, s[2:3]
	v_lshl_add_u64 v[74:75], v[58:59], 0, s[2:3]
	global_load_dwordx4 v[58:61], v[58:59], off nt
	s_nop 0
	global_load_dwordx4 v[70:73], v[74:75], off nt
	v_lshl_add_u64 v[74:75], v[74:75], 0, s[2:3]
	v_lshl_add_u64 v[86:87], v[74:75], 0, s[2:3]
	global_load_dwordx4 v[74:77], v[74:75], off nt
	s_nop 0
	global_load_dwordx4 v[78:81], v[86:87], off nt
	v_lshl_add_u64 v[86:87], v[86:87], 0, s[2:3]
	v_lshl_add_u64 v[98:99], v[86:87], 0, s[2:3]
	v_lshl_add_u64 v[106:107], v[98:99], 0, s[2:3]
	v_lshl_add_u64 v[110:111], v[106:107], 0, s[2:3]
	v_lshl_add_u64 v[114:115], v[110:111], 0, s[2:3]
	v_lshl_add_u64 v[118:119], v[114:115], 0, s[2:3]
	v_lshl_add_u64 v[122:123], v[118:119], 0, s[2:3]
	v_lshl_add_u64 v[126:127], v[122:123], 0, s[2:3]
	v_lshl_add_u64 v[130:131], v[126:127], 0, s[2:3]
	global_load_dwordx4 v[86:89], v[86:87], off nt
	s_nop 0
	global_load_dwordx4 v[94:97], v[98:99], off nt
	s_nop 0
	global_load_dwordx4 v[98:101], v[106:107], off nt
	s_nop 0
	global_load_dwordx4 v[106:109], v[110:111], off nt
	s_nop 0
	global_load_dwordx4 v[110:113], v[114:115], off nt
	s_nop 0
	global_load_dwordx4 v[114:117], v[118:119], off nt
	s_nop 0
	global_load_dwordx4 v[118:121], v[122:123], off nt
	s_nop 0
	global_load_dwordx4 v[122:125], v[126:127], off nt
	s_nop 0
	global_load_dwordx4 v[126:129], v[130:131], off nt
	v_lshl_add_u64 v[130:131], v[130:131], 0, s[2:3]
	global_load_dwordx4 v[130:133], v[130:131], off nt

.LBB0_66:
	s_lshr_b32 s61, s54, 6
	v_cvt_f32_u32_e32 v139, s61
	s_sub_i32 s60, 0, s61
	s_abs_i32 s3, s73
	s_ashr_i32 s2, s73, 31
	v_rcp_iflag_f32_e32 v139, v139
	v_mov_b32_e32 v143, 1.0
	v_mul_f32_e32 v139, 0x4f7ffffe, v139
	v_cvt_u32_f32_e32 v142, v139
	v_mov_b32_e32 v139, 1.0
	v_readfirstlane_b32 s62, v142
	s_mul_i32 s60, s60, s62
	s_mul_hi_u32 s60, s62, s60
	s_add_i32 s62, s62, s60
	s_mul_hi_u32 s60, s3, s62
	s_mul_i32 s62, s60, s61
	s_sub_i32 s3, s3, s62
	s_add_i32 s63, s60, 1
	s_sub_i32 s62, s3, s61
	s_cmp_ge_u32 s3, s61
	s_cselect_b32 s60, s63, s60
	s_cselect_b32 s3, s62, s3
	s_add_i32 s62, s60, 1
	s_cmp_ge_u32 s3, s61
	s_cselect_b32 s3, s62, s60
	s_xor_b32 s3, s3, s2
	s_sub_i32 s76, s3, s2
	s_lshl_b32 s60, s76, 6
	v_or_b32_e32 v144, s60, v137
	s_cmp_lg_u64 s[44:45], 0
	s_cselect_b64 s[62:63], -1, 0
	s_cmp_eq_u64 s[44:45], 0
	v_ashrrev_i32_e32 v145, 31, v144
	s_cbranch_scc1 .Lp0i_nog_A
	s_cmp_lg_u64 s[58:59], 0
	s_cbranch_scc0 .Lgh_a_w0
	s_waitcnt vmcnt(16)
	v_mov_b32_e32 v143, v203
	s_branch .LBB0_68
.Lgh_a_w0:
	s_waitcnt vmcnt(0)
	v_mov_b32_e32 v143, v203
	s_branch .LBB0_68

.LBB0_102:
	s_waitcnt lgkmcnt(0)
	v_add_u32_e32 v201, v178, v177
	v_add_u32_e32 v200, v179, v177
	s_waitcnt lgkmcnt(3)
	ds_read_b64_tr_b16 v[142:143], v201
	s_waitcnt lgkmcnt(2)
	ds_read_b64_tr_b16 v[146:147], v201 offset:32
	ds_read_b64_tr_b16 v[150:151], v201 offset:64
	ds_read_b64_tr_b16 v[154:155], v201 offset:96
	ds_read_b64_tr_b16 v[144:145], v201 offset:576
	s_waitcnt lgkmcnt(5)
	ds_read_b64_tr_b16 v[148:149], v201 offset:608
	ds_read_b64_tr_b16 v[152:153], v201 offset:640
	ds_read_b64_tr_b16 v[156:157], v201 offset:672
	ds_read_b64_tr_b16 v[158:159], v200
	ds_read_b64_tr_b16 v[162:163], v200 offset:32
	ds_read_b64_tr_b16 v[166:167], v200 offset:64
	ds_read_b64_tr_b16 v[170:171], v200 offset:96
	ds_read_b64_tr_b16 v[160:161], v200 offset:576
	ds_read_b64_tr_b16 v[164:165], v200 offset:608
	ds_read_b64_tr_b16 v[168:169], v200 offset:640
	ds_read_b64_tr_b16 v[172:173], v200 offset:672
	v_add_u32_e32 v198, v180, v181
	v_add_u32_e32 v199, v180, v182
	s_waitcnt lgkmcnt(0)
	s_waitcnt lgkmcnt(11)
	ds_write_b128 v198, v[142:145]
	s_waitcnt lgkmcnt(4)
	ds_write_b128 v199, v[158:161]
	ds_write_b128 v198, v[146:149] offset:2304
	s_waitcnt lgkmcnt(5)
	ds_write_b128 v199, v[162:165] offset:2304
	ds_write_b128 v198, v[150:153] offset:4608
	s_waitcnt lgkmcnt(6)
	ds_write_b128 v199, v[166:169] offset:4608
	ds_write_b128 v198, v[154:157] offset:6912
	s_waitcnt lgkmcnt(7)
	ds_write_b128 v199, v[170:173] offset:6912
	s_waitcnt lgkmcnt(0)
	v_add_u32_e32 v197, v184, v185
	v_or_b32_e32 v139, s2, v183
	s_ashr_i32 s3, s2, 31
	ds_read_b128 v[142:145], v197
	s_mul_i32 s76, s3, s74
	v_mad_u64_u32 v[146:147], s[62:63], v139, s74, 0
	s_ashr_i32 s61, s60, 31
	v_add_u32_e32 v147, s76, v147
	v_lshl_add_u64 v[146:147], v[146:147], 1, s[36:37]
	s_lshl_b64 s[60:61], s[60:61], 1
	v_lshl_add_u64 v[146:147], v[146:147], 0, s[60:61]
	v_lshl_add_u64 v[150:151], v[146:147], 0, v[140:141]
	v_or_b32_e32 v139, s2, v186
	ds_read_b128 v[146:149], v197 offset:1152
	s_waitcnt lgkmcnt(1)
	global_store_dwordx4 v[150:151], v[142:145], off
	s_nop 1
	v_mad_u64_u32 v[142:143], s[62:63], v139, s74, 0
	v_add_u32_e32 v143, s76, v143
	v_lshl_add_u64 v[142:143], v[142:143], 1, s[36:37]
	v_lshl_add_u64 v[142:143], v[142:143], 0, s[60:61]
	v_lshl_add_u64 v[142:143], v[142:143], 0, v[140:141]
	v_or_b32_e32 v139, s2, v187
	s_waitcnt lgkmcnt(0)
	global_store_dwordx4 v[142:143], v[146:149], off
	ds_read_b128 v[142:145], v197 offset:2304
	s_nop 0
	v_mad_u64_u32 v[146:147], s[62:63], v139, s74, 0
	v_add_u32_e32 v147, s76, v147
	v_lshl_add_u64 v[146:147], v[146:147], 1, s[36:37]
	v_lshl_add_u64 v[146:147], v[146:147], 0, s[60:61]
	v_lshl_add_u64 v[150:151], v[146:147], 0, v[140:141]
	v_or_b32_e32 v139, s2, v188
	ds_read_b128 v[146:149], v197 offset:3456
	s_waitcnt lgkmcnt(1)
	global_store_dwordx4 v[150:151], v[142:145], off
	s_nop 1
	v_mad_u64_u32 v[142:143], s[62:63], v139, s74, 0
	v_add_u32_e32 v143, s76, v143
	v_lshl_add_u64 v[142:143], v[142:143], 1, s[36:37]
	v_lshl_add_u64 v[142:143], v[142:143], 0, s[60:61]
	v_lshl_add_u64 v[142:143], v[142:143], 0, v[140:141]
	v_or_b32_e32 v139, s2, v189
	s_waitcnt lgkmcnt(0)
	global_store_dwordx4 v[142:143], v[146:149], off
	ds_read_b128 v[142:145], v197 offset:4608
	s_nop 0
	v_mad_u64_u32 v[146:147], s[62:63], v139, s74, 0
	v_add_u32_e32 v147, s76, v147
	v_lshl_add_u64 v[146:147], v[146:147], 1, s[36:37]
	v_lshl_add_u64 v[146:147], v[146:147], 0, s[60:61]
	v_lshl_add_u64 v[150:151], v[146:147], 0, v[140:141]
	v_or_b32_e32 v139, s2, v190
	ds_read_b128 v[146:149], v197 offset:5760
	s_waitcnt lgkmcnt(1)
	global_store_dwordx4 v[150:151], v[142:145], off
	s_nop 1
	v_mad_u64_u32 v[142:143], s[62:63], v139, s74, 0
	v_add_u32_e32 v143, s76, v143
	v_lshl_add_u64 v[142:143], v[142:143], 1, s[36:37]
	v_lshl_add_u64 v[142:143], v[142:143], 0, s[60:61]
	v_lshl_add_u64 v[142:143], v[142:143], 0, v[140:141]
	v_or_b32_e32 v139, s2, v191
	s_waitcnt lgkmcnt(0)
	global_store_dwordx4 v[142:143], v[146:149], off
	ds_read_b128 v[142:145], v197 offset:6912
	s_nop 0
	v_mad_u64_u32 v[146:147], s[62:63], v139, s74, 0
	v_add_u32_e32 v147, s76, v147
	v_lshl_add_u64 v[146:147], v[146:147], 1, s[36:37]
	v_lshl_add_u64 v[146:147], v[146:147], 0, s[60:61]
	v_lshl_add_u64 v[150:151], v[146:147], 0, v[140:141]
	v_or_b32_e32 v139, s2, v192
	ds_read_b128 v[146:149], v197 offset:8064
	s_waitcnt lgkmcnt(1)
	global_store_dwordx4 v[150:151], v[142:145], off
	s_nop 1
	v_mad_u64_u32 v[142:143], s[2:3], v139, s74, 0
	v_add_u32_e32 v143, s76, v143
	v_lshl_add_u64 v[142:143], v[142:143], 1, s[36:37]
	v_lshl_add_u64 v[142:143], v[142:143], 0, s[60:61]
	v_lshl_add_u64 v[142:143], v[142:143], 0, v[140:141]
	s_waitcnt lgkmcnt(0)
	global_store_dwordx4 v[142:143], v[146:149], off
	s_cmp_eq_u64 s[58:59], 0
	s_cbranch_scc1 .Lgh_b_skip
	s_cmp_eq_u64 s[56:57], 0
	s_cbranch_scc1 .Lgh_b_skip
	global_load_dword v203, v246, s[56:57]
	global_load_dword v204, v246, s[56:57] offset:16
	global_load_dword v205, v246, s[56:57] offset:32
	global_load_dword v206, v246, s[56:57] offset:48
	global_load_dword v207, v246, s[56:57] offset:64
	global_load_dword v208, v246, s[56:57] offset:80
	global_load_dword v209, v246, s[56:57] offset:96
	global_load_dword v210, v246, s[56:57] offset:112
	global_load_dword v211, v246, s[56:57] offset:128
	global_load_dword v212, v246, s[56:57] offset:144
	global_load_dword v213, v246, s[56:57] offset:160
	global_load_dword v215, v246, s[56:57] offset:176
	global_load_dword v216, v246, s[56:57] offset:192
	global_load_dword v242, v246, s[56:57] offset:208
	global_load_dword v243, v246, s[56:57] offset:224
	global_load_dword v244, v246, s[56:57] offset:240
.Lgh_b_skip:
	s_add_i32 s76, s55, s40
	s_waitcnt lgkmcnt(0)
	s_cmp_ge_i32 s76, s72
	s_cselect_b64 s[60:61], -1, 0
	s_and_b64 vcc, exec, s[60:61]
	s_cbranch_vccz .LBB0_104
	s_andn2_b64 vcc, exec, s[58:59]
	s_cbranch_vccnz .LBB0_46
	s_branch .LBB0_120

.LBB0_119:
	s_lshr_b32 s62, s54, 6
	v_cvt_f32_u32_e32 v6, s62
	s_sub_i32 s78, 0, s62
	s_abs_i32 s77, s73
	s_ashr_i32 s63, s73, 31
	v_rcp_iflag_f32_e32 v6, v6
	s_mov_b32 s55, s35
	v_mov_b32_e32 v139, v141
	v_mul_f32_e32 v6, 0x4f7ffffe, v6
	v_cvt_u32_f32_e32 v6, v6
	s_nop 0
	v_readfirstlane_b32 s79, v6
	s_mul_i32 s78, s78, s79
	s_mul_hi_u32 s78, s79, s78
	s_add_i32 s79, s79, s78
	s_mul_hi_u32 s78, s77, s79
	s_mul_i32 s79, s78, s62
	s_sub_i32 s77, s77, s79
	s_add_i32 s80, s78, 1
	s_sub_i32 s79, s77, s62
	s_cmp_ge_u32 s77, s62
	s_cselect_b32 s78, s80, s78
	s_cselect_b32 s77, s79, s77
	s_add_i32 s79, s78, 1
	s_cmp_ge_u32 s77, s62
	s_cselect_b32 s77, s79, s78
	s_xor_b32 s77, s77, s63
	s_sub_i32 s63, s77, s63
	s_mul_i32 s62, s63, s62
	s_lshl_b32 s63, s63, 6
	s_sub_i32 s77, s73, s62
	v_or_b32_e32 v6, s63, v137
	v_lshlrev_b32_e32 v245, 2, v6
	s_ashr_i32 s62, s63, 31
	s_mul_i32 s78, s62, s54
	v_mad_u64_u32 v[6:7], s[62:63], v6, s54, 0
	v_add_u32_e32 v7, s78, v7
	s_waitcnt lgkmcnt(0)
	v_lshl_add_u64 v[6:7], v[6:7], 2, s[2:3]
	s_lshl_b32 s2, s77, 6
	s_ashr_i32 s3, s2, 31
	v_lshl_add_u64 v[6:7], s[2:3], 2, v[6:7]
	v_lshl_add_u64 v[6:7], v[6:7], 0, v[138:139]
	s_lshl_b64 s[2:3], s[54:55], 4
	v_lshl_add_u64 v[14:15], v[6:7], 0, s[2:3]
	global_load_dwordx4 v[6:9], v[6:7], off nt
	s_nop 0
	global_load_dwordx4 v[10:13], v[14:15], off nt
	v_lshl_add_u64 v[14:15], v[14:15], 0, s[2:3]
	v_lshl_add_u64 v[22:23], v[14:15], 0, s[2:3]
	global_load_dwordx4 v[14:17], v[14:15], off nt
	s_nop 0
	global_load_dwordx4 v[18:21], v[22:23], off nt
	v_lshl_add_u64 v[22:23], v[22:23], 0, s[2:3]
	v_lshl_add_u64 v[30:31], v[22:23], 0, s[2:3]
	global_load_dwordx4 v[22:25], v[22:23], off nt
	s_nop 0
	global_load_dwordx4 v[26:29], v[30:31], off nt
	v_lshl_add_u64 v[30:31], v[30:31], 0, s[2:3]
	v_lshl_add_u64 v[38:39], v[30:31], 0, s[2:3]
	v_lshl_add_u64 v[46:47], v[38:39], 0, s[2:3]
	v_lshl_add_u64 v[50:51], v[46:47], 0, s[2:3]
	v_lshl_add_u64 v[62:63], v[50:51], 0, s[2:3]
	v_lshl_add_u64 v[66:67], v[62:63], 0, s[2:3]
	v_lshl_add_u64 v[82:83], v[66:67], 0, s[2:3]
	v_lshl_add_u64 v[90:91], v[82:83], 0, s[2:3]
	v_lshl_add_u64 v[102:103], v[90:91], 0, s[2:3]
	global_load_dwordx4 v[30:33], v[30:31], off nt
	s_nop 0
	global_load_dwordx4 v[34:37], v[38:39], off nt
	s_nop 0
	global_load_dwordx4 v[38:41], v[46:47], off nt
	s_nop 0
	global_load_dwordx4 v[46:49], v[50:51], off nt
	s_nop 0
	global_load_dwordx4 v[50:53], v[62:63], off nt
	s_nop 0
	global_load_dwordx4 v[62:65], v[66:67], off nt
	s_nop 0
	global_load_dwordx4 v[66:69], v[82:83], off nt
	s_nop 0
	global_load_dwordx4 v[82:85], v[90:91], off nt
	s_nop 0
	global_load_dwordx4 v[90:93], v[102:103], off nt
	v_lshl_add_u64 v[102:103], v[102:103], 0, s[2:3]
	global_load_dwordx4 v[102:105], v[102:103], off nt
	s_andn2_b64 vcc, exec, s[58:59]
	s_cbranch_vccnz .LBB0_46

.LBB0_122:
	s_ashr_i32 s55, s34, 6
	s_abs_i32 s2, s55
	v_cvt_f32_u32_e32 v139, s2
	s_sub_i32 s59, 0, s2
	s_abs_i32 s3, s47
	s_xor_b32 s58, s47, s55
	v_rcp_iflag_f32_e32 v142, v139
	s_ashr_i32 s58, s58, 31
	v_mov_b32_e32 v139, 1.0
	v_mov_b32_e32 v143, 1.0
	v_mul_f32_e32 v142, 0x4f7ffffe, v142
	v_cvt_u32_f32_e32 v142, v142
	s_nop 0
	v_readfirstlane_b32 s62, v142
	s_mul_i32 s59, s59, s62
	s_mul_hi_u32 s59, s62, s59
	s_add_i32 s62, s62, s59
	s_mul_hi_u32 s59, s3, s62
	s_mul_i32 s62, s59, s2
	s_sub_i32 s3, s3, s62
	s_add_i32 s63, s59, 1
	s_sub_i32 s62, s3, s2
	s_cmp_ge_u32 s3, s2
	s_cselect_b32 s59, s63, s59
	s_cselect_b32 s3, s62, s3
	s_add_i32 s62, s59, 1
	s_cmp_ge_u32 s3, s2
	s_cselect_b32 s2, s62, s59
	s_xor_b32 s2, s2, s58
	s_sub_i32 s59, s2, s58
	s_lshl_b32 s58, s59, 6
	v_or_b32_e32 v144, s58, v137
	s_cmp_lg_u64 s[56:57], 0
	s_cselect_b64 s[62:63], -1, 0
	s_cmp_eq_u64 s[56:57], 0
	v_ashrrev_i32_e32 v145, 31, v144
	s_cbranch_scc1 .Lp0i_nog_B
	s_cmp_lg_u64 s[60:61], 0
	s_cbranch_scc1 .Lgh_b_w0
	s_waitcnt vmcnt(16)
	v_mov_b32_e32 v143, v203
	s_branch .LBB0_124
